# gate prefetch loads (mLSTM wave 6, DeltaNet prep wave 5) no longer waited immediately: raw value kept in the register, converted at use one unit later
# speedup vs baseline: 1.0274x; 1.0101x over previous
.LBB0_227:
	s_or_b64 exec, exec, s[46:47]
	v_mov_b32_e32 v0, v1
	v_mov_b64_e32 v[34:35], v[0:1]
	s_and_saveexec_b64 s[46:47], s[12:13]
	s_cbranch_execz .LBB0_229
	v_or_b32_e32 v0, vcc_lo, v64
	v_mov_b64_e32 v[2:3], s[96:97]
	v_mad_u64_u32 v[2:3], s[60:61], v0, s87, v[2:3]
	v_mad_i32_i24 v3, vcc_hi, v169, v3
	s_lshl_b32 s62, s59, 1
	v_lshl_add_u64 v[2:3], v[2:3], 0, s[62:63]
	v_add_co_u32_e32 v2, vcc, 0x2000, v2
	s_nop 1
	v_addc_co_u32_e32 v3, vcc, 0, v3, vcc
	global_load_ushort v35, v[2:3], off
	s_nop 0
	global_load_ushort v34, v[2:3], off offset:16

.LBB0_237:
	s_waitcnt vmcnt(0)
	v_lshlrev_b32_e32 v35, 16, v35
	v_lshlrev_b32_e32 v34, 16, v34
	s_waitcnt vmcnt(5)
	v_add_f32_e32 v0, v201, v35
	s_waitcnt vmcnt(4)
	v_add_f32_e32 v2, v202, v34
	s_mov_b32 s44, 0xc1a00000
	ds_write_b32 v93, v0
	v_xor_b32_e32 v0, 0x80000000, v2
	v_cmp_ngt_f32_e32 vcc, s44, v2
	s_and_saveexec_b64 s[60:61], vcc
	s_cbranch_execz .LBB0_239
	v_mul_f32_e32 v0, 0xbfb8aa3b, v2
	v_exp_f32_e32 v0, v0
	s_mov_b32 s44, 0x7f800000
	v_add_f32_e32 v60, 1.0, v0
	v_frexp_mant_f32_e32 v62, v60
	v_cvt_f64_f32_e32 v[2:3], v60
	v_frexp_exp_i32_f64_e32 v2, v[2:3]
	v_cmp_gt_f32_e32 vcc, s64, v62
	v_add_f32_e32 v61, -1.0, v60
	v_sub_f32_e32 v63, v61, v60
	v_subbrev_co_u32_e32 v114, vcc, 0, v2, vcc
	v_sub_u32_e32 v2, 0, v114
	v_sub_f32_e32 v61, v0, v61
	v_add_f32_e32 v63, 1.0, v63
	v_ldexp_f32 v3, v60, v2
	v_add_f32_e32 v61, v61, v63
	v_add_f32_e32 v60, -1.0, v3
	v_add_f32_e32 v62, 1.0, v3
	v_ldexp_f32 v2, v61, v2
	v_add_f32_e32 v61, 1.0, v60
	v_add_f32_e32 v63, -1.0, v62
	v_sub_f32_e32 v61, v3, v61
	v_sub_f32_e32 v3, v3, v63
	v_add_f32_e32 v61, v2, v61
	v_add_f32_e32 v2, v2, v3
	v_add_f32_e32 v115, v62, v2
	v_rcp_f32_e32 v117, v115
	v_sub_f32_e32 v3, v115, v62
	v_sub_f32_e32 v116, v2, v3
	v_add_f32_e32 v3, v60, v61
	v_mul_f32_e32 v119, v3, v117
	v_sub_f32_e32 v2, v3, v60
	v_mul_f32_e32 v60, v115, v119
	v_fma_f32 v62, v119, v115, -v60
	v_fmac_f32_e32 v62, v119, v116
	v_sub_f32_e32 v118, v61, v2
	v_add_f32_e32 v2, v60, v62
	v_sub_f32_e32 v61, v3, v2
	v_pk_add_f32 v[112:113], v[2:3], v[60:61] neg_lo:[0,1] neg_hi:[0,1]
	v_mov_b32_e32 v63, v2
	v_pk_add_f32 v[2:3], v[112:113], v[62:63] neg_lo:[0,1] neg_hi:[0,1]
	v_cmp_neq_f32_e32 vcc, s44, v0
	v_add_f32_e32 v3, v118, v3
	v_add_f32_e32 v2, v2, v3
	v_add_f32_e32 v3, v61, v2
	v_mul_f32_e32 v118, v117, v3
	v_mul_f32_e32 v60, v115, v118
	v_fma_f32 v62, v118, v115, -v60
	v_fmac_f32_e32 v62, v118, v116
	v_sub_f32_e32 v61, v61, v3
	v_add_f32_e32 v115, v2, v61
	v_add_f32_e32 v2, v60, v62
	v_sub_f32_e32 v61, v3, v2
	v_pk_add_f32 v[112:113], v[2:3], v[60:61] neg_lo:[0,1] neg_hi:[0,1]
	v_mov_b32_e32 v63, v2
	v_pk_add_f32 v[2:3], v[112:113], v[62:63] neg_lo:[0,1] neg_hi:[0,1]
	s_mov_b32 s44, 0x33800000
	v_add_f32_e32 v3, v115, v3
	v_add_f32_e32 v2, v2, v3
	v_add_f32_e32 v3, v119, v118
	v_add_f32_e32 v2, v61, v2
	v_sub_f32_e32 v60, v3, v119
	v_mul_f32_e32 v2, v117, v2
	v_sub_f32_e32 v60, v118, v60
	v_add_f32_e32 v60, v60, v2
	v_add_f32_e32 v62, v3, v60
	v_mul_f32_e32 v63, v62, v62
	v_fmamk_f32 v2, v63, 0x3e9b6dac, v162
	v_fmaak_f32 v145, v63, v2, 0x3f2aaada
	v_cvt_f32_i32_e32 v2, v114
	v_sub_f32_e32 v3, v62, v3
	v_sub_f32_e32 v3, v60, v3
	v_ldexp_f32 v112, v3, 1
	v_mul_f32_e32 v3, v62, v63
	v_ldexp_f32 v61, v62, 1
	v_pk_mul_f32 v[62:63], v[2:3], v[144:145]
	s_nop 0
	v_fma_f32 v60, v2, s70, -v62
	v_fmac_f32_e32 v60, 0xb102e308, v2
	v_pk_add_f32 v[2:3], v[62:63], v[60:61]
	s_nop 0
	v_sub_f32_e32 v61, v3, v61
	v_sub_f32_e32 v61, v63, v61
	v_add_f32_e32 v113, v112, v61
	v_mov_b32_e32 v112, v62
	v_pk_add_f32 v[62:63], v[2:3], v[62:63] neg_lo:[0,1] neg_hi:[0,1]
	v_pk_add_f32 v[114:115], v[2:3], v[112:113]
	v_mov_b32_e32 v61, v2
	v_mov_b32_e32 v63, v115
	v_pk_add_f32 v[116:117], v[60:61], v[62:63] neg_lo:[0,1] neg_hi:[0,1]
	v_pk_add_f32 v[60:61], v[60:61], v[62:63]
	v_mov_b32_e32 v112, v113
	v_pk_add_f32 v[62:63], v[60:61], v[2:3] op_sel:[1,0] op_sel_hi:[0,1] neg_lo:[0,1] neg_hi:[0,1]
	v_pk_add_f32 v[118:119], v[114:115], v[62:63] op_sel_hi:[1,0] neg_lo:[0,1] neg_hi:[0,1]
	v_mov_b32_e32 v114, v115
	v_mov_b32_e32 v115, v61
	v_pk_mov_b32 v[62:63], v[2:3], v[62:63] op_sel:[1,0]
	v_mov_b32_e32 v113, v2
	v_pk_add_f32 v[62:63], v[114:115], v[62:63] neg_lo:[0,1] neg_hi:[0,1]
	v_mov_b32_e32 v118, v116
	v_pk_add_f32 v[2:3], v[112:113], v[62:63] neg_lo:[0,1] neg_hi:[0,1]
	v_mov_b32_e32 v117, v61
	v_pk_add_f32 v[62:63], v[118:119], v[2:3]
	s_nop 0
	v_pk_add_f32 v[112:113], v[62:63], v[62:63] op_sel:[0,1] op_sel_hi:[1,0]
	s_nop 0
	v_pk_add_f32 v[60:61], v[60:61], v[112:113] op_sel:[1,0] op_sel_hi:[0,1]
	v_mov_b32_e32 v63, v60
	v_pk_add_f32 v[114:115], v[62:63], v[116:117] neg_lo:[0,1] neg_hi:[0,1]
	v_mov_b32_e32 v3, v112
	v_sub_f32_e32 v61, v62, v114
	v_pk_add_f32 v[2:3], v[2:3], v[114:115] neg_lo:[0,1] neg_hi:[0,1]
	v_sub_f32_e32 v61, v116, v61
	v_add_f32_e32 v2, v2, v61
	v_add_f32_e32 v2, v2, v3
	v_add_f32_e32 v2, v60, v2
	v_cndmask_b32_e32 v2, v172, v2, vcc
	v_cmp_ngt_f32_e32 vcc, -1.0, v0
	s_nop 1
	v_cndmask_b32_e32 v2, v173, v2, vcc
	v_cmp_neq_f32_e32 vcc, -1.0, v0
	s_nop 1
	v_cndmask_b32_e32 v2, v163, v2, vcc
	v_cmp_lt_f32_e64 vcc, |v0|, s44
	s_nop 1
	v_cndmask_b32_e32 v0, v2, v0, vcc

.LBB0_243:
	v_lshl_add_u64 v[2:3], v[104:105], 0, s[76:77]
	v_add_co_u32_e32 v2, vcc, 0x808a000, v2
	s_nop 1
	v_addc_co_u32_e32 v3, vcc, 0, v3, vcc
	global_load_ushort v35, v[2:3], off
	s_nop 0
	global_load_ushort v34, v[2:3], off offset:16

.LBB0_321:
	s_or_b64 exec, exec, s[10:11]
	v_mov_b32_e32 v0, v1
	v_cmp_eq_u32_e32 vcc, 5, v9
	v_mov_b64_e32 v[40:41], v[0:1]
	s_and_saveexec_b64 s[10:11], vcc
	s_cbranch_execz .LBB0_323
	v_or_b32_e32 v0, s8, v8
	v_mov_b64_e32 v[2:3], s[24:25]
	v_mad_u64_u32 v[2:3], s[8:9], v0, s87, v[2:3]
	v_add_u32_e32 v3, s13, v3
	s_lshl_b32 s62, s2, 1
	v_lshl_add_u64 v[2:3], v[2:3], 0, s[62:63]
	v_add_co_u32_e32 v2, vcc, 0x2000, v2
	s_nop 1
	v_addc_co_u32_e32 v3, vcc, 0, v3, vcc
	global_load_ushort v41, v[2:3], off
	s_nop 0
	global_load_ushort v40, v[2:3], off offset:16

.LBB0_524:
	v_mov_b32_e32 v80, v68
	s_bfe_u32 s16, s36, 0x30006
	v_lshlrev_b32_e32 v0, 2, v80
	v_and_b32_e32 v42, 0xfffffc00, v0
	v_ashrrev_i32_e32 v43, 31, v42
	v_lshlrev_b64 v[14:15], 2, v[42:43]
	v_and_b32_e32 v85, 31, v80
	s_lshl_b32 s62, s16, 9
	v_lshl_add_u64 v[6:7], s[28:29], 0, v[14:15]
	v_lshl_add_u64 v[2:3], s[26:27], 0, v[14:15]
	v_lshlrev_b32_e32 v0, 4, v85
	v_lshl_add_u64 v[6:7], v[6:7], 0, s[62:63]
	v_lshl_add_u64 v[2:3], v[2:3], 0, s[62:63]
	v_lshl_add_u64 v[6:7], v[6:7], 0, v[0:1]
	v_lshl_add_u64 v[10:11], s[30:31], 0, v[14:15]
	v_lshl_add_u64 v[2:3], v[2:3], 0, v[0:1]
	global_load_dwordx4 v[6:9], v[6:7], off
	v_lshl_add_u64 v[10:11], v[10:11], 0, s[62:63]
	v_lshl_add_u64 v[14:15], s[34:35], 0, v[14:15]
	global_load_dwordx4 v[2:5], v[2:3], off
	v_lshl_add_u64 v[10:11], v[10:11], 0, v[0:1]
	v_lshl_add_u64 v[14:15], v[14:15], 0, s[62:63]
	global_load_dwordx4 v[10:13], v[10:11], off
	v_lshl_add_u64 v[14:15], v[14:15], 0, v[0:1]
	global_load_dwordx4 v[14:17], v[14:15], off
	s_ashr_i32 s37, s36, 31
	v_and_b32_e32 v81, 63, v80
	s_add_u32 s6, s42, s62
	s_addc_u32 s7, s43, 0
	v_lshlrev_b32_e32 v43, 3, v81
	global_load_dwordx2 v[44:45], v43, s[6:7]
	s_add_u32 s6, s75, s62
	s_addc_u32 s7, s52, 0
	global_load_dwordx2 v[46:47], v43, s[6:7]
	s_add_u32 s6, s53, s62
	s_waitcnt vmcnt(14)
	v_lshlrev_b32_e32 v64, 16, v18
	v_and_b32_e32 v65, 0xffff0000, v18
	s_addc_u32 s7, s54, 0
	v_lshlrev_b32_e32 v56, 16, v20
	v_and_b32_e32 v57, 0xffff0000, v20
	global_load_dwordx2 v[48:49], v43, s[6:7]
	s_add_u32 s6, s55, s62
	v_lshlrev_b32_e32 v60, 16, v22
	v_and_b32_e32 v61, 0xffff0000, v22
	s_addc_u32 s7, s60, 0
	s_waitcnt vmcnt(14)
	v_lshlrev_b32_e32 v52, 16, v24
	v_and_b32_e32 v53, 0xffff0000, v24
	global_load_dwordx2 v[50:51], v43, s[6:7]
	v_lshlrev_b32_e32 v66, 16, v19
	v_and_b32_e32 v67, 0xffff0000, v19
	v_lshlrev_b32_e32 v58, 16, v21
	v_and_b32_e32 v59, 0xffff0000, v21
	v_lshlrev_b32_e32 v62, 16, v23
	v_and_b32_e32 v63, 0xffff0000, v23
	v_lshlrev_b32_e32 v54, 16, v25
	v_and_b32_e32 v55, 0xffff0000, v25
	s_movk_i32 s2, 0x100
	v_lshrrev_b32_e32 v84, 2, v80
	v_cmp_gt_u32_e64 s[8:9], s2, v80
	s_add_i32 s2, 0, 0x16000
	v_and_b32_e32 v82, 56, v84
	v_mov_b32_e32 v0, s2
	v_cndmask_b32_e64 v0, v0, 0, s[8:9]
	v_lshlrev_b32_e32 v86, 3, v85
	s_barrier
	v_ashrrev_i32_e32 v43, 6, v80
	v_cmp_lt_u32_e32 vcc, s70, v80
	s_waitcnt vmcnt(7)
	v_pk_mul_f32 v[88:89], v[6:7], v[64:65]
	v_pk_mul_f32 v[90:91], v[8:9], v[66:67]
	s_waitcnt vmcnt(6)
	v_pk_fma_f32 v[56:57], v[2:3], v[56:57], v[88:89]
	v_pk_fma_f32 v[58:59], v[4:5], v[58:59], v[90:91]
	v_pk_mul_f32 v[90:91], v[8:9], v[62:63]
	s_waitcnt vmcnt(5)
	v_pk_fma_f32 v[56:57], v[10:11], v[60:61], v[56:57]
	v_pk_fma_f32 v[58:59], v[12:13], v[62:63], v[58:59]
	s_waitcnt vmcnt(4)
	v_pk_fma_f32 v[56:57], v[14:15], v[52:53], v[56:57]
	v_pk_fma_f32 v[58:59], v[16:17], v[54:55], v[58:59]
	v_mul_f32_e32 v83, 0xbfb8aa3b, v56
	v_exp_f32_e32 v83, v83
	v_pk_fma_f32 v[66:67], v[4:5], v[66:67], v[90:91]
	v_pk_mul_f32 v[90:91], v[8:9], v[54:55]
	v_pk_fma_f32 v[66:67], v[12:13], v[54:55], v[66:67]
	v_add_f32_e32 v83, 1.0, v83
	v_rcp_f32_e32 v88, v83
	v_mul_f32_e32 v83, 0xbfb8aa3b, v57
	v_exp_f32_e32 v83, v83
	v_pk_fma_f32 v[62:63], v[4:5], v[62:63], v[90:91]
	v_add_f32_e32 v83, 1.0, v83
	v_rcp_f32_e32 v89, v83
	v_or_b32_e32 v83, 3, v82
	v_pk_mul_f32 v[56:57], v[56:57], v[88:89]
	s_nop 0
	v_cvt_pk_bf16_f32 v56, v56, v57
	v_mul_f32_e32 v57, 0xbfb8aa3b, v58
	v_exp_f32_e32 v57, v57
	s_nop 0
	v_add_f32_e32 v57, 1.0, v57
	v_rcp_f32_e32 v88, v57
	v_mul_f32_e32 v57, 0xbfb8aa3b, v59
	v_exp_f32_e32 v57, v57
	s_nop 0
	v_add_f32_e32 v57, 1.0, v57
	v_rcp_f32_e32 v89, v57
	s_nop 0
	v_pk_mul_f32 v[58:59], v[58:59], v[88:89]
	s_nop 0
	v_cvt_pk_bf16_f32 v57, v58, v59
	v_mul_u32_u24_e32 v58, 0x110, v83
	v_add3_u32 v87, v0, v58, v86
	v_pk_mul_f32 v[88:89], v[6:7], v[60:61]
	v_add_u32_e32 v58, 0xfffffcd0, v87
	v_pk_fma_f32 v[64:65], v[2:3], v[64:65], v[88:89]
	ds_write_b64 v58, v[56:57]
	v_lshlrev_b32_e32 v56, 16, v26
	v_and_b32_e32 v57, 0xffff0000, v26
	v_pk_fma_f32 v[64:65], v[10:11], v[52:53], v[64:65]
	v_lshlrev_b32_e32 v58, 16, v27
	v_pk_fma_f32 v[64:65], v[14:15], v[56:57], v[64:65]
	v_and_b32_e32 v59, 0xffff0000, v27
	v_mul_f32_e32 v88, 0xbfb8aa3b, v64
	v_mul_f32_e32 v89, 0xbfb8aa3b, v65
	v_exp_f32_e32 v88, v88
	v_exp_f32_e32 v89, v89
	v_pk_fma_f32 v[66:67], v[16:17], v[58:59], v[66:67]
	v_pk_fma_f32 v[62:63], v[12:13], v[58:59], v[62:63]
	v_add_f32_e32 v88, 1.0, v88
	v_add_f32_e32 v89, 1.0, v89
	v_rcp_f32_e32 v88, v88
	v_rcp_f32_e32 v89, v89
	v_pk_mul_f32 v[90:91], v[8:9], v[58:59]
	v_pk_mul_f32 v[64:65], v[64:65], v[88:89]
	s_nop 0
	v_cvt_pk_bf16_f32 v64, v64, v65
	v_mul_f32_e32 v65, 0xbfb8aa3b, v66
	v_exp_f32_e32 v65, v65
	v_pk_fma_f32 v[54:55], v[4:5], v[54:55], v[90:91]
	v_add_f32_e32 v65, 1.0, v65
	v_rcp_f32_e32 v88, v65
	v_mul_f32_e32 v65, 0xbfb8aa3b, v67
	v_exp_f32_e32 v65, v65
	s_nop 0
	v_add_f32_e32 v65, 1.0, v65
	v_rcp_f32_e32 v89, v65
	s_nop 0
	v_pk_mul_f32 v[66:67], v[66:67], v[88:89]
	v_pk_mul_f32 v[88:89], v[6:7], v[52:53]
	v_cvt_pk_bf16_f32 v65, v66, v67
	v_add_u32_e32 v66, 0xfffffde0, v87
	v_pk_fma_f32 v[60:61], v[2:3], v[60:61], v[88:89]
	ds_write_b64 v66, v[64:65]
	v_lshlrev_b32_e32 v64, 16, v28
	v_and_b32_e32 v65, 0xffff0000, v28
	v_pk_fma_f32 v[60:61], v[10:11], v[56:57], v[60:61]
	v_lshlrev_b32_e32 v66, 16, v29
	v_pk_fma_f32 v[60:61], v[14:15], v[64:65], v[60:61]
	v_and_b32_e32 v67, 0xffff0000, v29
	v_mul_f32_e32 v88, 0xbfb8aa3b, v60
	v_mul_f32_e32 v89, 0xbfb8aa3b, v61
	v_exp_f32_e32 v88, v88
	v_exp_f32_e32 v89, v89
	v_pk_fma_f32 v[62:63], v[16:17], v[66:67], v[62:63]
	v_pk_fma_f32 v[54:55], v[12:13], v[66:67], v[54:55]
	v_add_f32_e32 v88, 1.0, v88
	v_add_f32_e32 v89, 1.0, v89
	v_rcp_f32_e32 v88, v88
	v_rcp_f32_e32 v89, v89
	v_pk_mul_f32 v[90:91], v[6:7], v[64:65]
	v_pk_mul_f32 v[92:93], v[8:9], v[66:67]
	v_pk_mul_f32 v[60:61], v[60:61], v[88:89]
	s_nop 0
	v_cvt_pk_bf16_f32 v60, v60, v61
	v_mul_f32_e32 v61, 0xbfb8aa3b, v62
	v_exp_f32_e32 v61, v61
	v_pk_fma_f32 v[58:59], v[4:5], v[58:59], v[92:93]
	v_add_f32_e32 v61, 1.0, v61
	v_rcp_f32_e32 v88, v61
	v_mul_f32_e32 v61, 0xbfb8aa3b, v63
	v_exp_f32_e32 v61, v61
	s_nop 0
	v_add_f32_e32 v61, 1.0, v61
	v_rcp_f32_e32 v89, v61
	s_nop 0
	v_pk_mul_f32 v[62:63], v[62:63], v[88:89]
	v_pk_mul_f32 v[88:89], v[6:7], v[56:57]
	v_cvt_pk_bf16_f32 v61, v62, v63
	v_add_u32_e32 v62, 0xfffffef0, v87
	v_pk_fma_f32 v[52:53], v[2:3], v[52:53], v[88:89]
	ds_write_b64 v62, v[60:61]
	v_lshlrev_b32_e32 v60, 16, v30
	v_and_b32_e32 v61, 0xffff0000, v30
	v_pk_fma_f32 v[52:53], v[10:11], v[64:65], v[52:53]
	v_lshlrev_b32_e32 v62, 16, v31
	v_pk_fma_f32 v[52:53], v[14:15], v[60:61], v[52:53]
	v_and_b32_e32 v63, 0xffff0000, v31
	v_mul_f32_e32 v88, 0xbfb8aa3b, v52
	v_mul_f32_e32 v89, 0xbfb8aa3b, v53
	v_exp_f32_e32 v88, v88
	v_exp_f32_e32 v89, v89
	v_pk_fma_f32 v[54:55], v[16:17], v[62:63], v[54:55]
	v_pk_fma_f32 v[56:57], v[2:3], v[56:57], v[90:91]
	v_add_f32_e32 v88, 1.0, v88
	v_add_f32_e32 v89, 1.0, v89
	v_rcp_f32_e32 v88, v88
	v_rcp_f32_e32 v89, v89
	v_pk_fma_f32 v[56:57], v[10:11], v[60:61], v[56:57]
	v_pk_fma_f32 v[58:59], v[12:13], v[62:63], v[58:59]
	v_pk_mul_f32 v[52:53], v[52:53], v[88:89]
	s_nop 0
	v_cvt_pk_bf16_f32 v88, v52, v53
	v_mul_f32_e32 v52, 0xbfb8aa3b, v54
	v_mul_f32_e32 v53, 0xbfb8aa3b, v55
	v_exp_f32_e32 v52, v52
	v_exp_f32_e32 v53, v53
	v_add_f32_e32 v52, 1.0, v52
	v_add_f32_e32 v53, 1.0, v53
	v_rcp_f32_e32 v52, v52
	v_rcp_f32_e32 v53, v53
	s_nop 0
	v_pk_mul_f32 v[52:53], v[54:55], v[52:53]
	s_nop 0
	v_cvt_pk_bf16_f32 v89, v52, v53
	v_lshlrev_b32_e32 v52, 16, v32
	v_and_b32_e32 v53, 0xffff0000, v32
	v_pk_fma_f32 v[56:57], v[14:15], v[52:53], v[56:57]
	v_lshlrev_b32_e32 v54, 16, v33
	v_mul_f32_e32 v90, 0xbfb8aa3b, v56
	v_mul_f32_e32 v91, 0xbfb8aa3b, v57
	v_exp_f32_e32 v90, v90
	v_exp_f32_e32 v91, v91
	v_and_b32_e32 v55, 0xffff0000, v33
	v_pk_fma_f32 v[58:59], v[16:17], v[54:55], v[58:59]
	v_add_f32_e32 v90, 1.0, v90
	v_add_f32_e32 v91, 1.0, v91
	v_rcp_f32_e32 v90, v90
	v_rcp_f32_e32 v91, v91
	s_nop 0
	v_pk_mul_f32 v[56:57], v[56:57], v[90:91]
	s_nop 0
	v_cvt_pk_bf16_f32 v56, v56, v57
	v_mul_f32_e32 v57, 0xbfb8aa3b, v58
	v_exp_f32_e32 v57, v57
	s_nop 0
	v_add_f32_e32 v57, 1.0, v57
	v_rcp_f32_e32 v90, v57
	v_mul_f32_e32 v57, 0xbfb8aa3b, v59
	v_exp_f32_e32 v57, v57
	s_nop 0
	v_add_f32_e32 v57, 1.0, v57
	v_rcp_f32_e32 v91, v57
	s_nop 0
	v_pk_mul_f32 v[58:59], v[58:59], v[90:91]
	s_nop 0
	v_cvt_pk_bf16_f32 v57, v58, v59
	ds_write2_b64 v87, v[88:89], v[56:57] offset1:34
	v_pk_mul_f32 v[88:89], v[6:7], v[60:61]
	v_lshlrev_b32_e32 v56, 16, v34
	v_pk_fma_f32 v[64:65], v[2:3], v[64:65], v[88:89]
	v_and_b32_e32 v57, 0xffff0000, v34
	v_pk_fma_f32 v[64:65], v[10:11], v[52:53], v[64:65]
	v_pk_mul_f32 v[90:91], v[8:9], v[62:63]
	v_pk_fma_f32 v[64:65], v[14:15], v[56:57], v[64:65]
	v_pk_fma_f32 v[66:67], v[4:5], v[66:67], v[90:91]
	v_mul_f32_e32 v87, 0xbfb8aa3b, v64
	v_exp_f32_e32 v87, v87
	v_lshlrev_b32_e32 v58, 16, v35
	v_and_b32_e32 v59, 0xffff0000, v35
	v_pk_fma_f32 v[66:67], v[12:13], v[54:55], v[66:67]
	v_add_f32_e32 v87, 1.0, v87
	v_rcp_f32_e32 v88, v87
	v_mul_f32_e32 v87, 0xbfb8aa3b, v65
	v_exp_f32_e32 v87, v87
	v_pk_fma_f32 v[66:67], v[16:17], v[58:59], v[66:67]
	v_pk_mul_f32 v[90:91], v[8:9], v[54:55]
	v_pk_mul_f32 v[8:9], v[8:9], v[58:59]
	v_add_f32_e32 v87, 1.0, v87
	v_rcp_f32_e32 v89, v87
	v_pk_fma_f32 v[62:63], v[4:5], v[62:63], v[90:91]
	v_and_b32_e32 v87, 0xffff0000, v37
	v_pk_fma_f32 v[62:63], v[12:13], v[58:59], v[62:63]
	v_pk_mul_f32 v[64:65], v[64:65], v[88:89]
	v_pk_fma_f32 v[4:5], v[4:5], v[54:55], v[8:9]
	v_cvt_pk_bf16_f32 v64, v64, v65
	v_mul_f32_e32 v65, 0xbfb8aa3b, v66
	v_exp_f32_e32 v65, v65
	s_nop 0
	v_add_f32_e32 v65, 1.0, v65
	v_rcp_f32_e32 v88, v65
	v_mul_f32_e32 v65, 0xbfb8aa3b, v67
	v_exp_f32_e32 v65, v65
	s_nop 0
	v_add_f32_e32 v65, 1.0, v65
	v_rcp_f32_e32 v89, v65
	s_nop 0
	v_pk_mul_f32 v[66:67], v[66:67], v[88:89]
	v_pk_mul_f32 v[88:89], v[6:7], v[52:53]
	v_cvt_pk_bf16_f32 v65, v66, v67
	v_mul_u32_u24_e32 v66, 0x110, v82
	v_pk_fma_f32 v[60:61], v[2:3], v[60:61], v[88:89]
	v_add3_u32 v0, v0, v66, v86
	v_lshlrev_b32_e32 v66, 16, v36
	v_and_b32_e32 v67, 0xffff0000, v36
	v_pk_fma_f32 v[60:61], v[10:11], v[56:57], v[60:61]
	v_lshlrev_b32_e32 v86, 16, v37
	v_pk_fma_f32 v[60:61], v[14:15], v[66:67], v[60:61]
	v_pk_fma_f32 v[62:63], v[16:17], v[86:87], v[62:63]
	v_mul_f32_e32 v88, 0xbfb8aa3b, v60
	v_mul_f32_e32 v89, 0xbfb8aa3b, v61
	v_exp_f32_e32 v88, v88
	v_exp_f32_e32 v89, v89
	v_pk_mul_f32 v[6:7], v[6:7], v[56:57]
	v_pk_fma_f32 v[4:5], v[12:13], v[86:87], v[4:5]
	v_add_f32_e32 v88, 1.0, v88
	v_add_f32_e32 v89, 1.0, v89
	v_rcp_f32_e32 v88, v88
	v_rcp_f32_e32 v89, v89
	v_pk_fma_f32 v[2:3], v[2:3], v[52:53], v[6:7]
	v_pk_mul_f32 v[60:61], v[60:61], v[88:89]
	s_nop 0
	v_cvt_pk_bf16_f32 v60, v60, v61
	v_mul_f32_e32 v61, 0xbfb8aa3b, v62
	v_exp_f32_e32 v61, v61
	v_pk_fma_f32 v[2:3], v[10:11], v[66:67], v[2:3]
	v_add_f32_e32 v61, 1.0, v61
	v_rcp_f32_e32 v88, v61
	v_mul_f32_e32 v61, 0xbfb8aa3b, v63
	v_exp_f32_e32 v61, v61
	s_nop 0
	v_add_f32_e32 v61, 1.0, v61
	v_rcp_f32_e32 v89, v61
	s_nop 0
	v_pk_mul_f32 v[62:63], v[62:63], v[88:89]
	s_nop 0
	v_cvt_pk_bf16_f32 v61, v62, v63
	ds_write2_b64 v0, v[64:65], v[60:61] offset0:170 offset1:204
	v_lshlrev_b32_e32 v60, 16, v38
	v_and_b32_e32 v61, 0xffff0000, v38
	v_pk_fma_f32 v[2:3], v[14:15], v[60:61], v[2:3]
	v_lshlrev_b32_e32 v62, 16, v39
	v_mul_f32_e32 v6, 0xbfb8aa3b, v2
	v_mul_f32_e32 v7, 0xbfb8aa3b, v3
	v_exp_f32_e32 v6, v6
	v_exp_f32_e32 v7, v7
	v_and_b32_e32 v63, 0xffff0000, v39
	v_pk_fma_f32 v[4:5], v[16:17], v[62:63], v[4:5]
	v_add_f32_e32 v6, 1.0, v6
	v_add_f32_e32 v7, 1.0, v7
	v_rcp_f32_e32 v6, v6
	v_rcp_f32_e32 v7, v7
	s_nop 0
	v_pk_mul_f32 v[2:3], v[2:3], v[6:7]
	s_nop 0
	v_cvt_pk_bf16_f32 v2, v2, v3
	v_mul_f32_e32 v3, 0xbfb8aa3b, v4
	v_exp_f32_e32 v3, v3
	s_nop 0
	v_add_f32_e32 v3, 1.0, v3
	v_rcp_f32_e32 v6, v3
	v_mul_f32_e32 v3, 0xbfb8aa3b, v5
	v_exp_f32_e32 v3, v3
	s_nop 0
	v_add_f32_e32 v3, 1.0, v3
	v_rcp_f32_e32 v7, v3
	s_nop 0
	v_pk_mul_f32 v[4:5], v[4:5], v[6:7]
	s_nop 0
	v_cvt_pk_bf16_f32 v3, v4, v5
	ds_write_b64 v0, v[2:3] offset:1904
	v_lshlrev_b32_e32 v4, 16, v69
	v_and_b32_e32 v5, 0xffff0000, v69
	v_lshlrev_b32_e32 v2, 16, v70
	v_and_b32_e32 v3, 0xffff0000, v70
	s_waitcnt vmcnt(2)
	v_pk_mul_f32 v[12:13], v[46:47], v[4:5]
	v_lshlrev_b32_e32 v6, 16, v72
	v_and_b32_e32 v7, 0xffff0000, v72
	v_pk_fma_f32 v[2:3], v[44:45], v[2:3], v[12:13]
	v_lshlrev_b32_e32 v8, 16, v71
	v_and_b32_e32 v9, 0xffff0000, v71
	s_waitcnt vmcnt(1)
	v_pk_fma_f32 v[2:3], v[48:49], v[6:7], v[2:3]
	v_lshlrev_b32_e32 v10, 3, v43
	s_waitcnt vmcnt(0)
	v_pk_fma_f32 v[2:3], v[50:51], v[8:9], v[2:3]
	s_movk_i32 s6, 0x110
	v_mul_f32_e32 v11, 0xbfb8aa3b, v2
	v_exp_f32_e32 v11, v11
	v_lshlrev_b32_e32 v0, 2, v81
	v_pk_mul_f32 v[14:15], v[46:47], v[6:7]
	s_movk_i32 s7, 0x880
	v_add_f32_e32 v11, 1.0, v11
	v_rcp_f32_e32 v12, v11
	v_mul_f32_e32 v11, 0xbfb8aa3b, v3
	v_exp_f32_e32 v11, v11
	v_pk_fma_f32 v[4:5], v[44:45], v[4:5], v[14:15]
	v_add_f32_e32 v11, 1.0, v11
	v_rcp_f32_e32 v13, v11
	v_pk_fma_f32 v[4:5], v[48:49], v[8:9], v[4:5]
	v_pk_mul_f32 v[2:3], v[2:3], v[12:13]
	v_or_b32_e32 v12, 3, v10
	v_cvt_pk_bf16_f32 v2, v2, v3
	v_mul_lo_u32 v3, v12, s6
	v_readlane_b32 s6, v244, 12
	s_nop 1
	v_add3_u32 v11, s6, v3, v0
	v_add_u32_e32 v3, 0xfffffcd0, v11
	ds_write_b32 v3, v2
	v_lshlrev_b32_e32 v2, 16, v74
	v_and_b32_e32 v3, 0xffff0000, v74
	v_pk_fma_f32 v[4:5], v[50:51], v[2:3], v[4:5]
	s_nop 0
	v_mul_f32_e32 v13, 0xbfb8aa3b, v4
	v_exp_f32_e32 v13, v13
	s_nop 0
	v_add_f32_e32 v13, 1.0, v13
	v_rcp_f32_e32 v14, v13
	v_mul_f32_e32 v13, 0xbfb8aa3b, v5
	v_exp_f32_e32 v13, v13
	s_nop 0
	v_add_f32_e32 v13, 1.0, v13
	v_rcp_f32_e32 v15, v13
	s_nop 0
	v_pk_mul_f32 v[4:5], v[4:5], v[14:15]
	v_pk_mul_f32 v[14:15], v[46:47], v[8:9]
	v_cvt_pk_bf16_f32 v4, v4, v5
	v_add_u32_e32 v5, 0xfffffde0, v11
	v_pk_fma_f32 v[6:7], v[44:45], v[6:7], v[14:15]
	ds_write_b32 v5, v4
	v_lshlrev_b32_e32 v4, 16, v73
	v_and_b32_e32 v5, 0xffff0000, v73
	v_pk_fma_f32 v[6:7], v[48:49], v[2:3], v[6:7]
	s_nop 0
	v_pk_fma_f32 v[6:7], v[50:51], v[4:5], v[6:7]
	s_nop 0
	v_mul_f32_e32 v13, 0xbfb8aa3b, v6
	v_exp_f32_e32 v13, v13
	s_nop 0
	v_add_f32_e32 v13, 1.0, v13
	v_rcp_f32_e32 v14, v13
	v_mul_f32_e32 v13, 0xbfb8aa3b, v7
	v_exp_f32_e32 v13, v13
	s_nop 0
	v_add_f32_e32 v13, 1.0, v13
	v_rcp_f32_e32 v15, v13
	s_nop 0
	v_pk_mul_f32 v[6:7], v[6:7], v[14:15]
	v_pk_mul_f32 v[14:15], v[46:47], v[2:3]
	v_cvt_pk_bf16_f32 v6, v6, v7
	v_add_u32_e32 v7, 0xfffffef0, v11
	v_pk_fma_f32 v[8:9], v[44:45], v[8:9], v[14:15]
	ds_write_b32 v7, v6
	v_lshlrev_b32_e32 v6, 16, v76
	v_and_b32_e32 v7, 0xffff0000, v76
	v_pk_fma_f32 v[8:9], v[48:49], v[4:5], v[8:9]
	s_nop 0
	v_pk_fma_f32 v[8:9], v[50:51], v[6:7], v[8:9]
	s_nop 0
	v_mul_f32_e32 v13, 0xbfb8aa3b, v8
	v_exp_f32_e32 v13, v13
	s_nop 0
	v_add_f32_e32 v13, 1.0, v13
	v_rcp_f32_e32 v14, v13
	v_mul_f32_e32 v13, 0xbfb8aa3b, v9
	v_exp_f32_e32 v13, v13
	s_nop 0
	v_add_f32_e32 v13, 1.0, v13
	v_rcp_f32_e32 v15, v13
	s_nop 0
	v_pk_mul_f32 v[8:9], v[8:9], v[14:15]
	v_pk_mul_f32 v[14:15], v[46:47], v[4:5]
	v_cvt_pk_bf16_f32 v13, v8, v9
	v_pk_fma_f32 v[2:3], v[44:45], v[2:3], v[14:15]
	v_lshlrev_b32_e32 v8, 16, v75
	v_and_b32_e32 v9, 0xffff0000, v75
	v_pk_fma_f32 v[2:3], v[48:49], v[6:7], v[2:3]
	s_nop 0
	v_pk_fma_f32 v[2:3], v[50:51], v[8:9], v[2:3]
	s_nop 0
	v_mul_f32_e32 v14, 0xbfb8aa3b, v2
	v_mul_f32_e32 v15, 0xbfb8aa3b, v3
	v_exp_f32_e32 v14, v14
	v_exp_f32_e32 v15, v15
	v_add_f32_e32 v14, 1.0, v14
	v_add_f32_e32 v15, 1.0, v15
	v_rcp_f32_e32 v14, v14
	v_rcp_f32_e32 v15, v15
	s_nop 0
	v_pk_mul_f32 v[2:3], v[2:3], v[14:15]
	v_pk_mul_f32 v[14:15], v[46:47], v[6:7]
	v_cvt_pk_bf16_f32 v2, v2, v3
	v_pk_fma_f32 v[4:5], v[44:45], v[4:5], v[14:15]
	ds_write2_b32 v11, v13, v2 offset1:68
	v_lshlrev_b32_e32 v2, 16, v78
	v_and_b32_e32 v3, 0xffff0000, v78
	v_pk_fma_f32 v[4:5], v[48:49], v[8:9], v[4:5]
	s_nop 0
	v_pk_fma_f32 v[4:5], v[50:51], v[2:3], v[4:5]
	s_nop 0
	v_mul_f32_e32 v11, 0xbfb8aa3b, v4
	v_exp_f32_e32 v11, v11
	s_nop 0
	v_add_f32_e32 v11, 1.0, v11
	v_rcp_f32_e32 v14, v11
	v_mul_f32_e32 v11, 0xbfb8aa3b, v5
	v_exp_f32_e32 v11, v11
	s_nop 0
	v_add_f32_e32 v11, 1.0, v11
	v_rcp_f32_e32 v15, v11
	s_nop 0
	v_pk_mul_f32 v[4:5], v[4:5], v[14:15]
	v_pk_mul_f32 v[14:15], v[46:47], v[8:9]
	v_cvt_pk_bf16_f32 v11, v4, v5
	v_mul_lo_u32 v4, v43, s7
	v_pk_fma_f32 v[6:7], v[44:45], v[6:7], v[14:15]
	v_add3_u32 v0, s6, v4, v0
	v_lshlrev_b32_e32 v4, 16, v77
	v_and_b32_e32 v5, 0xffff0000, v77
	v_pk_fma_f32 v[6:7], v[48:49], v[2:3], v[6:7]
	v_pk_mul_f32 v[2:3], v[46:47], v[2:3]
	v_pk_fma_f32 v[6:7], v[50:51], v[4:5], v[6:7]
	v_pk_fma_f32 v[2:3], v[44:45], v[8:9], v[2:3]
	v_mul_f32_e32 v13, 0xbfb8aa3b, v6
	v_exp_f32_e32 v13, v13
	v_pk_fma_f32 v[2:3], v[48:49], v[4:5], v[2:3]
	v_cmp_eq_u32_e64 s[6:7], 5, v43
	v_add_f32_e32 v13, 1.0, v13
	v_rcp_f32_e32 v14, v13
	v_mul_f32_e32 v13, 0xbfb8aa3b, v7
	v_exp_f32_e32 v13, v13
	s_nop 0
	v_add_f32_e32 v13, 1.0, v13
	v_rcp_f32_e32 v15, v13
	s_nop 0
	v_pk_mul_f32 v[6:7], v[6:7], v[14:15]
	s_nop 0
	v_cvt_pk_bf16_f32 v6, v6, v7
	v_add_u32_e32 v7, 0x400, v0
	ds_write2_b32 v7, v11, v6 offset0:84 offset1:152
	v_lshlrev_b32_e32 v6, 16, v79
	v_and_b32_e32 v7, 0xffff0000, v79
	v_pk_fma_f32 v[2:3], v[50:51], v[6:7], v[2:3]
	s_nop 0
	v_mul_f32_e32 v4, 0xbfb8aa3b, v2
	v_mul_f32_e32 v5, 0xbfb8aa3b, v3
	v_exp_f32_e32 v4, v4
	v_exp_f32_e32 v5, v5
	v_add_f32_e32 v4, 1.0, v4
	v_add_f32_e32 v5, 1.0, v5
	v_rcp_f32_e32 v4, v4
	v_rcp_f32_e32 v5, v5
	s_nop 0
	v_pk_mul_f32 v[2:3], v[2:3], v[4:5]
	s_nop 0
	v_cvt_pk_bf16_f32 v2, v2, v3
	ds_write_b32 v0, v2 offset:1904
	s_and_saveexec_b64 s[12:13], s[6:7]
	s_cbranch_execz .LBB0_529
	s_load_dwordx4 s[44:47], s[0:1], 0x48
	s_or_b32 s10, s16, s74
	s_ashr_i32 s11, s10, 31
	s_lshl_b64 s[10:11], s[10:11], 2
	s_waitcnt lgkmcnt(0)
	s_add_u32 s14, s44, s10
	s_addc_u32 s15, s45, s11
	s_add_u32 s10, s46, s10
	s_addc_u32 s11, s47, s11
	global_load_dword v0, v1, s[14:15]
	global_load_dword v2, v1, s[10:11]
	s_mov_b32 s10, 0x41a00000
	s_waitcnt vmcnt(0)
	v_lshlrev_b32_e32 v40, 16, v40
	v_add_f32_e32 v2, v40, v2
	v_cmp_nlt_f32_e64 s[10:11], s10, v2
	s_and_saveexec_b64 s[14:15], s[10:11]
	s_cbranch_execz .LBB0_527
	v_mul_f32_e32 v2, 0x3fb8aa3b, v2
	v_exp_f32_e32 v11, v2
	s_mov_b32 s10, 0x3f2aaaab
	v_add_f32_e32 v4, 1.0, v11
	v_frexp_mant_f32_e32 v6, v4
	v_cvt_f64_f32_e32 v[2:3], v4
	v_frexp_exp_i32_f64_e32 v2, v[2:3]
	v_cmp_gt_f32_e64 s[10:11], s10, v6
	v_add_f32_e32 v5, -1.0, v4
	v_sub_f32_e32 v7, v5, v4
	v_subbrev_co_u32_e64 v13, s[10:11], 0, v2, s[10:11]
	v_sub_u32_e32 v2, 0, v13
	v_sub_f32_e32 v5, v11, v5
	v_add_f32_e32 v7, 1.0, v7
	v_ldexp_f32 v3, v4, v2
	v_add_f32_e32 v5, v5, v7
	v_add_f32_e32 v4, -1.0, v3
	v_add_f32_e32 v6, 1.0, v3
	v_ldexp_f32 v2, v5, v2
	v_add_f32_e32 v5, 1.0, v4
	v_add_f32_e32 v7, -1.0, v6
	v_sub_f32_e32 v5, v3, v5
	v_sub_f32_e32 v3, v3, v7
	v_add_f32_e32 v5, v2, v5
	v_add_f32_e32 v2, v2, v3
	v_add_f32_e32 v14, v6, v2
	v_rcp_f32_e32 v16, v14
	v_sub_f32_e32 v3, v14, v6
	v_sub_f32_e32 v15, v2, v3
	v_add_f32_e32 v3, v4, v5
	v_mul_f32_e32 v44, v3, v16
	v_sub_f32_e32 v2, v3, v4
	v_mul_f32_e32 v4, v14, v44
	v_fma_f32 v6, v44, v14, -v4
	v_fmac_f32_e32 v6, v44, v15
	v_sub_f32_e32 v17, v5, v2
	v_add_f32_e32 v2, v4, v6
	v_sub_f32_e32 v5, v3, v2
	v_pk_add_f32 v[8:9], v[2:3], v[4:5] neg_lo:[0,1] neg_hi:[0,1]
	v_mov_b32_e32 v7, v2
	v_pk_add_f32 v[2:3], v[8:9], v[6:7] neg_lo:[0,1] neg_hi:[0,1]
	s_mov_b32 s10, 0x3f317218
	v_add_f32_e32 v3, v17, v3
	v_add_f32_e32 v2, v2, v3
	v_add_f32_e32 v3, v5, v2
	v_mul_f32_e32 v17, v16, v3
	v_mul_f32_e32 v4, v14, v17
	v_fma_f32 v6, v17, v14, -v4
	v_fmac_f32_e32 v6, v17, v15
	v_sub_f32_e32 v5, v5, v3
	v_add_f32_e32 v14, v2, v5
	v_add_f32_e32 v2, v4, v6
	v_sub_f32_e32 v5, v3, v2
	v_pk_add_f32 v[8:9], v[2:3], v[4:5] neg_lo:[0,1] neg_hi:[0,1]
	v_mov_b32_e32 v7, v2
	v_pk_add_f32 v[2:3], v[8:9], v[6:7] neg_lo:[0,1] neg_hi:[0,1]
	s_nop 0
	v_add_f32_e32 v3, v14, v3
	v_add_f32_e32 v2, v2, v3
	v_add_f32_e32 v3, v44, v17
	v_add_f32_e32 v2, v5, v2
	v_sub_f32_e32 v4, v3, v44
	v_mul_f32_e32 v2, v16, v2
	v_sub_f32_e32 v4, v17, v4
	v_add_f32_e32 v4, v4, v2
	v_add_f32_e32 v6, v3, v4
	v_mul_f32_e32 v7, v6, v6
	v_fmamk_f32 v2, v7, 0x3e9b6dac, v162
	v_fmaak_f32 v145, v7, v2, 0x3f2aaada
	v_cvt_f32_i32_e32 v2, v13
	v_sub_f32_e32 v3, v6, v3
	v_sub_f32_e32 v3, v4, v3
	v_ldexp_f32 v8, v3, 1
	v_mul_f32_e32 v3, v6, v7
	v_ldexp_f32 v5, v6, 1
	v_pk_mul_f32 v[6:7], v[2:3], v[144:145]
	s_nop 0
	v_fma_f32 v4, v2, s10, -v6
	v_fmac_f32_e32 v4, 0xb102e308, v2
	v_pk_add_f32 v[2:3], v[6:7], v[4:5]
	s_mov_b32 s10, 0x7f800000
	v_sub_f32_e32 v5, v3, v5
	v_sub_f32_e32 v5, v7, v5
	v_add_f32_e32 v9, v8, v5
	v_mov_b32_e32 v8, v6
	v_pk_add_f32 v[6:7], v[2:3], v[6:7] neg_lo:[0,1] neg_hi:[0,1]
	v_pk_add_f32 v[14:15], v[2:3], v[8:9]
	v_mov_b32_e32 v5, v2
	v_mov_b32_e32 v7, v15
	v_pk_add_f32 v[16:17], v[4:5], v[6:7] neg_lo:[0,1] neg_hi:[0,1]
	v_pk_add_f32 v[4:5], v[4:5], v[6:7]
	v_mov_b32_e32 v8, v9
	v_pk_add_f32 v[6:7], v[4:5], v[2:3] op_sel:[1,0] op_sel_hi:[0,1] neg_lo:[0,1] neg_hi:[0,1]
	v_pk_add_f32 v[44:45], v[14:15], v[6:7] op_sel_hi:[1,0] neg_lo:[0,1] neg_hi:[0,1]
	v_mov_b32_e32 v14, v15
	v_mov_b32_e32 v15, v5
	v_pk_mov_b32 v[6:7], v[2:3], v[6:7] op_sel:[1,0]
	v_mov_b32_e32 v9, v2
	v_pk_add_f32 v[6:7], v[14:15], v[6:7] neg_lo:[0,1] neg_hi:[0,1]
	v_mov_b32_e32 v44, v16
	v_pk_add_f32 v[2:3], v[8:9], v[6:7] neg_lo:[0,1] neg_hi:[0,1]
	v_mov_b32_e32 v17, v5
	v_pk_add_f32 v[6:7], v[44:45], v[2:3]
	v_cmp_neq_f32_e64 s[10:11], s10, v11
	v_pk_add_f32 v[8:9], v[6:7], v[6:7] op_sel:[0,1] op_sel_hi:[1,0]
	s_nop 0
	v_pk_add_f32 v[4:5], v[4:5], v[8:9] op_sel:[1,0] op_sel_hi:[0,1]
	v_mov_b32_e32 v7, v4
	v_pk_add_f32 v[14:15], v[6:7], v[16:17] neg_lo:[0,1] neg_hi:[0,1]
	v_mov_b32_e32 v3, v8
	v_sub_f32_e32 v5, v6, v14
	v_pk_add_f32 v[2:3], v[2:3], v[14:15] neg_lo:[0,1] neg_hi:[0,1]
	v_sub_f32_e32 v5, v16, v5
	v_add_f32_e32 v2, v2, v5
	v_add_f32_e32 v2, v2, v3
	v_add_f32_e32 v2, v4, v2
	v_cndmask_b32_e64 v2, v172, v2, s[10:11]
	v_cmp_ngt_f32_e64 s[10:11], -1.0, v11
	s_nop 1
	v_cndmask_b32_e64 v2, v173, v2, s[10:11]
	v_cmp_neq_f32_e64 s[10:11], -1.0, v11
	s_nop 1
	v_cndmask_b32_e64 v2, v163, v2, s[10:11]
	s_mov_b32 s10, 0x33800000
	v_cmp_lt_f32_e64 s[10:11], |v11|, s10
	s_nop 1
	v_cndmask_b32_e64 v2, v2, v11, s[10:11]
.LBB0_527:
	s_or_b64 exec, exec, s[14:15]
	v_mul_f32_e32 v0, 0x3fb8aa3b, v0
	v_exp_f32_e32 v0, v0
	v_and_b32_e32 v4, 64, v168
	v_add_u32_e32 v5, -1, v168
	v_cmp_lt_i32_e64 s[10:11], v5, v4
	v_mul_f32_e64 v3, v2, -v0
	s_nop 0
	v_cndmask_b32_e64 v5, v5, v168, s[10:11]
	v_lshlrev_b32_e32 v5, 2, v5
	ds_bpermute_b32 v5, v5, v3
	v_cmp_eq_u32_e64 s[10:11], 0, v81
	s_waitcnt lgkmcnt(0)
	v_fma_f32 v0, v2, -v0, v5
	v_add_u32_e32 v2, -2, v168
	v_cndmask_b32_e64 v0, v0, v3, s[10:11]
	v_cmp_lt_i32_e64 s[10:11], v2, v4
	v_lshl_add_u32 v3, v81, 2, 0
	s_nop 0
	v_cndmask_b32_e64 v2, v2, v168, s[10:11]
	v_lshlrev_b32_e32 v2, 2, v2
	ds_bpermute_b32 v2, v2, v0
	v_cmp_gt_u32_e64 s[10:11], 2, v81
	s_waitcnt lgkmcnt(0)
	v_add_f32_e32 v2, v0, v2
	v_cndmask_b32_e64 v0, v2, v0, s[10:11]
	v_add_u32_e32 v2, -4, v168
	v_cmp_lt_i32_e64 s[10:11], v2, v4
	s_nop 1
	v_cndmask_b32_e64 v2, v2, v168, s[10:11]
	v_lshlrev_b32_e32 v2, 2, v2
	ds_bpermute_b32 v2, v2, v0
	v_cmp_gt_u32_e64 s[10:11], 4, v81
	s_waitcnt lgkmcnt(0)
	v_add_f32_e32 v2, v0, v2
	v_cndmask_b32_e64 v0, v2, v0, s[10:11]
	v_add_u32_e32 v2, -8, v168
	v_cmp_lt_i32_e64 s[10:11], v2, v4
	s_nop 1
	v_cndmask_b32_e64 v2, v2, v168, s[10:11]
	v_lshlrev_b32_e32 v2, 2, v2
	ds_bpermute_b32 v2, v2, v0
	v_cmp_gt_u32_e64 s[10:11], 8, v81
	s_waitcnt lgkmcnt(0)
	v_add_f32_e32 v2, v0, v2
	v_cndmask_b32_e64 v0, v2, v0, s[10:11]
	v_add_u32_e32 v2, -16, v168
	v_cmp_lt_i32_e64 s[10:11], v2, v4
	s_nop 1
	v_cndmask_b32_e64 v2, v2, v168, s[10:11]
	v_lshlrev_b32_e32 v2, 2, v2
	ds_bpermute_b32 v2, v2, v0
	v_cmp_gt_u32_e64 s[10:11], 16, v81
	s_waitcnt lgkmcnt(0)
	v_add_f32_e32 v2, v0, v2
	v_cndmask_b32_e64 v0, v2, v0, s[10:11]
	v_subrev_u32_e32 v2, 32, v168
	v_cmp_lt_i32_e64 s[10:11], v2, v4
	v_add_u32_e32 v4, 0x15c00, v3
	s_nop 0
	v_cndmask_b32_e64 v2, v2, v168, s[10:11]
	v_lshlrev_b32_e32 v2, 2, v2
	ds_bpermute_b32 v2, v2, v0
	v_cmp_gt_u32_e64 s[10:11], 32, v81
	s_waitcnt lgkmcnt(0)
	v_add_f32_e32 v2, v0, v2
	v_cndmask_b32_e64 v0, v2, v0, s[10:11]
	v_lshlrev_b32_e32 v41, 16, v41
	v_mul_f32_e32 v2, 0xbfb8aa3b, v41
	v_exp_f32_e32 v2, v2
	v_cmp_eq_u32_e64 s[10:11], 63, v81
	v_add_f32_e32 v2, 1.0, v2
	v_rcp_f32_e32 v2, v2
	ds_write_b32 v4, v2
	v_add_u32_e32 v2, 0x15d00, v3
	ds_write_b32 v2, v0
	v_mul_f32_e32 v0, 0x3fb8aa3b, v0
	v_exp_f32_e32 v0, v0
	v_add_u32_e32 v2, 0x15e00, v3
	ds_write_b32 v2, v0
	s_and_b64 exec, exec, s[10:11]
	s_cbranch_execz .LBB0_529
	s_lshl_b64 s[10:11], s[36:37], 2
	s_add_u32 s10, s40, s10
	s_addc_u32 s11, s41, s11
	global_store_dword v1, v0, s[10:11]

.LBB0_598:
	s_or_b64 exec, exec, s[10:11]
	s_and_saveexec_b64 s[10:11], s[6:7]
	s_cbranch_execz .LBB0_522
	v_or_b32_e32 v0, s8, v81
	v_mov_b64_e32 v[2:3], s[24:25]
	v_mad_u64_u32 v[2:3], s[6:7], v0, s87, v[2:3]
	v_add_u32_e32 v3, s14, v3
	s_lshl_b32 s62, s12, 1
	v_lshl_add_u64 v[2:3], v[2:3], 0, s[62:63]
	v_add_co_u32_e32 v2, vcc, 0x2000, v2
	s_nop 1
	v_addc_co_u32_e32 v3, vcc, 0, v3, vcc
	global_load_ushort v41, v[2:3], off
	s_nop 0
	global_load_ushort v40, v[2:3], off offset:16
	s_branch .LBB0_522
